# v122 with the converter rate limit raised to s_sleep 44 per weight item (traffic spread further over the GEMM1 phase)
# baseline (speedup 1.0000x reference)
.LBB0_80:
	s_cmp_lg_u32 s101, 2
	s_cbranch_scc1 .Lp0_nothr
	s_sleep 44
